# grid barrier release flattened: every workgroup polls the cross-XCC arrival counter instead of waiting for TOPGEN then XGEN
# baseline (speedup 1.0000x reference)
; __device__ __forceinline__ unsigned xb_ld(unsigned* p)              { return __hip_atomic_load(p, __ATOMIC_RELAXED, __HIP_MEMORY_SCOPE_AGENT); }
; __device__ __forceinline__ unsigned xb_add(unsigned* p, unsigned v) { return __hip_atomic_fetch_add(p, v, __ATOMIC_RELAXED, __HIP_MEMORY_SCOPE_AGENT); }
; #define XB_SPIN(cond, bar) do { unsigned _sp = 0; while (cond) { __builtin_amdgcn_s_sleep(1); \
;     if ((++_sp & 255u) == 0u) { if (xb_ld(&(bar)[XB_TMO])) break; if (_sp > XB_SPIN_CAP) { atomicAdd(&(bar)[XB_TMO], 1u); break; } } } } while (0)
; __device__ __forceinline__ void xcd_barrier(const XcdBarrier& b) {
;     ...
;         const unsigned old = xb_add(&bar[XB_XSUB(b.x)], 1u);
;         const unsigned gen = old / nloc;
;         if (old + 1u == (gen + 1u) * nloc) {
;     ...
;             XB_SPIN(xb_ld(&bar[XB_XGEN(b.x)]) == gen, bar);
.LBB0_721:
	s_or_b64 exec, exec, s[4:5]
	v_cvt_f32_u32_e32 v4, v2
	s_waitcnt vmcnt(0)
	v_readfirstlane_b32 s4, v3
	v_sub_u32_e32 v3, 0, v2
	v_rcp_iflag_f32_e32 v4, v4
	v_add_u32_e32 v5, s4, v1
	v_mul_f32_e32 v4, 0x4f7ffffe, v4
	v_cvt_u32_f32_e32 v4, v4
	v_mul_lo_u32 v1, v3, v4
	v_mul_hi_u32 v1, v4, v1
	v_add_u32_e32 v1, v4, v1
	v_mul_hi_u32 v1, v5, v1
	v_mul_lo_u32 v3, v1, v2
	v_sub_u32_e32 v3, v5, v3
	v_add_u32_e32 v4, 1, v1
	v_cmp_ge_u32_e32 vcc, v3, v2
	s_nop 1
	v_cndmask_b32_e32 v1, v1, v4, vcc
	v_sub_u32_e32 v4, v3, v2
	v_cndmask_b32_e32 v3, v3, v4, vcc
	v_add_u32_e32 v4, 1, v1
	v_cmp_ge_u32_e32 vcc, v3, v2
	v_add_u32_e32 v3, 1, v5
	s_nop 0
	v_cndmask_b32_e32 v1, v1, v4, vcc
	v_mul_lo_u32 v4, v2, v1
	v_add_u32_e32 v2, v4, v2
	v_cmp_ne_u32_e32 vcc, v3, v2
	s_and_saveexec_b64 s[4:5], vcc
	s_xor_b64 s[4:5], exec, s[4:5]
	s_cbranch_execz .LBB0_735
	v_readlane_b32 s10, v253, 48
	v_readlane_b32 s11, v253, 49
	s_waitcnt lgkmcnt(0)
	v_mad_u32_u24 v5, v1, v0, v0
	s_nop 3
	global_load_dword v0, v197, s[10:11] sc1
	s_waitcnt vmcnt(0)
	v_cmp_lt_u32_e32 vcc, v0, v5
	s_and_saveexec_b64 s[10:11], vcc
	s_cbranch_execz .LBB0_734
	s_mov_b32 s8, 1
	s_mov_b64 s[12:13], 0
	s_branch .LBB0_725

; __device__ __forceinline__ unsigned xb_ld(unsigned* p)              { return __hip_atomic_load(p, __ATOMIC_RELAXED, __HIP_MEMORY_SCOPE_AGENT); }
; #define XB_SPIN(cond, bar) do { unsigned _sp = 0; while (cond) { __builtin_amdgcn_s_sleep(1); \
;     if ((++_sp & 255u) == 0u) { if (xb_ld(&(bar)[XB_TMO])) break; if (_sp > XB_SPIN_CAP) { atomicAdd(&(bar)[XB_TMO], 1u); break; } } } } while (0)
; __device__ __forceinline__ void xcd_barrier(const XcdBarrier& b) {
;     ...
;             XB_SPIN(xb_ld(&bar[XB_XGEN(b.x)]) == gen, bar);
.LBB0_729:
	v_readlane_b32 s16, v253, 48
	v_readlane_b32 s17, v253, 49
	s_add_i32 s8, s8, 1
	s_mov_b64 s[18:19], -1
	s_nop 2
	global_load_dword v0, v197, s[16:17] sc1
	s_waitcnt vmcnt(0)
	v_cmp_ge_u32_e32 vcc, v0, v5
	s_orn2_b64 s[16:17], vcc, exec
	s_branch .LBB0_724

; __device__ __forceinline__ unsigned xb_ld(unsigned* p)              { return __hip_atomic_load(p, __ATOMIC_RELAXED, __HIP_MEMORY_SCOPE_AGENT); }
; __device__ __forceinline__ unsigned xb_add(unsigned* p, unsigned v) { return __hip_atomic_fetch_add(p, v, __ATOMIC_RELAXED, __HIP_MEMORY_SCOPE_AGENT); }
; #define XB_SPIN(cond, bar) do { unsigned _sp = 0; while (cond) { __builtin_amdgcn_s_sleep(1); \
;     if ((++_sp & 255u) == 0u) { if (xb_ld(&(bar)[XB_TMO])) break; if (_sp > XB_SPIN_CAP) { atomicAdd(&(bar)[XB_TMO], 1u); break; } } } } while (0)
; __device__ __forceinline__ void xcd_barrier(const XcdBarrier& b) {
;     ...
;             const unsigned og = xb_add(&bar[XB_TOP], 1u);
;             const unsigned tg = og / nx;
;             if (og + 1u == (tg + 1u) * nx) xb_add(&bar[XB_TOPGEN], 1u);
;             else XB_SPIN(xb_ld(&bar[XB_TOPGEN]) == tg, bar);
.LBB0_738:
	s_or_b64 exec, exec, s[10:11]
	s_waitcnt vmcnt(0)
	v_readfirstlane_b32 s4, v2
	v_cvt_f32_u32_e32 v2, v0
	v_sub_u32_e32 v3, 0, v0
	v_add_u32_e32 v1, s4, v1
	v_readlane_b32 s4, v253, 50
	v_rcp_iflag_f32_e32 v2, v2
	v_readlane_b32 s5, v253, 51
	s_mov_b64 s[10:11], -1
	v_mul_f32_e32 v2, 0x4f7ffffe, v2
	v_cvt_u32_f32_e32 v2, v2
	v_mul_lo_u32 v3, v3, v2
	v_mul_hi_u32 v3, v2, v3
	v_add_u32_e32 v2, v2, v3
	v_mul_hi_u32 v2, v1, v2
	v_mul_lo_u32 v3, v2, v0
	v_sub_u32_e32 v3, v1, v3
	v_cmp_ge_u32_e32 vcc, v3, v0
	v_add_u32_e32 v4, 1, v2
	v_add_u32_e32 v1, 1, v1
	v_cndmask_b32_e32 v2, v2, v4, vcc
	v_sub_u32_e32 v4, v3, v0
	v_cndmask_b32_e32 v3, v3, v4, vcc
	v_cmp_ge_u32_e32 vcc, v3, v0
	v_add_u32_e32 v3, 1, v2
	s_nop 0
	v_cndmask_b32_e32 v2, v2, v3, vcc
	v_mul_lo_u32 v3, v0, v2
	v_add_u32_e32 v0, v3, v0
	v_cmp_ne_u32_e32 vcc, v1, v0
	v_mov_b32_e32 v5, v0
	v_mov_b64_e32 v[0:1], s[4:5]
	s_and_saveexec_b64 s[4:5], vcc
	s_cbranch_execz .LBB0_750
	v_readlane_b32 s10, v253, 48
	v_readlane_b32 s11, v253, 49
	s_mov_b64 s[12:13], 0
	s_nop 3
	global_load_dword v0, v197, s[10:11] sc1
	s_waitcnt vmcnt(0)
	v_cmp_lt_u32_e32 vcc, v0, v5
	s_and_saveexec_b64 s[10:11], vcc
	s_cbranch_execz .LBB0_749
	s_mov_b32 s8, 1
	s_branch .LBB0_742
